# v93 + the cooperative-groups grid.sync after P0 replaced by a hand-written XCD-hierarchical barrier (generation 0 of the same counters the later barriers use), started by a ready tag workgroup 0 publi
# speedup vs baseline: 1.0277x; 1.0277x over previous
; __device__ __forceinline__ unsigned xb_ld(unsigned* p)              { return __hip_atomic_load(p, __ATOMIC_RELAXED, __HIP_MEMORY_SCOPE_AGENT); }
; __device__ __forceinline__ void xcd_barrier_complete(unsigned* bar, unsigned x, unsigned& nloc, unsigned& nx) {
;     const unsigned G = gridDim.x * gridDim.y * gridDim.z;
;     unsigned sum, cnt, mine, sp = 0u;
;     for (;;) {
;         sum = 0u; cnt = 0u; mine = 0u;
; #pragma unroll
;         for (unsigned j = 0; j < 16; ++j) { const unsigned c = xb_ld(&bar[XB_XCNT(j)]); sum += c; cnt += (c > 0u) ? 1u : 0u; mine = (j == x) ? c : mine; }
;         if (sum == G) break;
;         __builtin_amdgcn_s_sleep(1);
;         if ((++sp & 255u) == 0u) { if (xb_ld(&bar[XB_TMO])) break; if (sp > XB_SPIN_CAP) { atomicAdd(&bar[XB_TMO], 1u); break; } }
;     }
;     nloc = mine > 0u ? mine : 1u; nx = cnt > 0u ? cnt : 1u;
; }
; __device__ __forceinline__ void xcd_barrier(const XcdBarrier& b) {
;     asm volatile("s_waitcnt vmcnt(0)" ::: "memory");
;     __syncthreads();
;     if (threadIdx.x == 0) {
;         unsigned* bar = b.bar;
;         __builtin_amdgcn_s_waitcnt(0);
;         unsigned nloc = b.st[0], nx = b.st[1];
;         if (nloc == 0u) { xcd_barrier_complete(bar, b.x, nloc, nx); b.st[0] = nloc; b.st[1] = nx; }
;         const unsigned old = xb_add(&bar[XB_XSUB(b.x)], 1u);
;         const unsigned gen = old / nloc;
;         if (old + 1u == (gen + 1u) * nloc) {
;             __builtin_amdgcn_fence(__ATOMIC_RELEASE, "agent");
;             asm volatile("s_waitcnt vmcnt(0)" ::: "memory");
;             const unsigned og = xb_add(&bar[XB_TOP], 1u);
;             const unsigned tg = og / nx;
;             if (og + 1u == (tg + 1u) * nx) xb_add(&bar[XB_TOPGEN], 1u);
;             else XB_SPIN(xb_ld(&bar[XB_TOPGEN]) == tg, bar);
;             __builtin_amdgcn_fence(__ATOMIC_ACQUIRE, "agent");
;             xb_add(&bar[XB_XGEN(b.x)], 1u);
;             asm volatile("s_waitcnt vmcnt(0)" ::: "memory");
;         } else {
;             XB_SPIN(xb_ld(&bar[XB_XGEN(b.x)]) == gen, bar);
;             __builtin_amdgcn_fence(__ATOMIC_ACQUIRE, "agent");
;             asm volatile("s_waitcnt vmcnt(0)" ::: "memory");
;         }
; __global__ void __launch_bounds__(512) fwd_kernel(Params p_unused) {
;     ...
;     grid.sync();
;     const XcdBarrier xb = xcd_barrier_post(barw, xst);
.LBB0_58:
	s_or_b64 exec, exec, s[4:5]
	s_getreg_b32 s0, hwreg(HW_REG_XCC_ID, 0, 4)
	s_and_b32 s0, s0, 15
	v_writelane_b32 v252, s0, 5
	v_cmp_eq_u32_e64 s[4:5], 0, v172
	s_mov_b64 s[0:1], exec
	s_nop 0
	v_writelane_b32 v252, s4, 6
	s_nop 1
	v_writelane_b32 v252, s5, 7
	s_waitcnt vmcnt(0) lgkmcnt(0)
	s_barrier
	s_and_b64 s[4:5], s[0:1], s[4:5]
	s_mov_b64 exec, s[4:5]
	s_cbranch_execz .Lgb0_done
	buffer_inv sc1
	v_mov_b32_e32 v0, 0
	s_mov_b32 s15, 0
.Lgb0_tag:
	global_load_dwordx2 v[2:3], v0, s[84:85] sc1
	s_waitcnt vmcnt(0)
	v_readfirstlane_b32 s6, v2
	v_readfirstlane_b32 s7, v3
	s_cmp_eq_u32 s6, 0x600dc0de
	s_cbranch_scc0 .Lgb0_tag_wait
	s_cmp_eq_u32 s7, 0x5afe7a61
	s_cbranch_scc1 .Lgb0_tag_ok
.Lgb0_tag_wait:
	s_sleep 1
	s_add_u32 s15, s15, 1
	s_cmp_lt_u32 s15, 0x8000
	s_cbranch_scc1 .Lgb0_tag
.Lgb0_tag_ok:
	v_readlane_b32 s3, v252, 5
	s_lshl_b32 s8, s3, 8
	v_mov_b32_e32 v1, 1
	v_mov_b32_e32 v4, s8
	global_atomic_add v4, v1, s[84:85] offset:1024
	v_mov_b32_e32 v5, 0x1000
.Lgb0_census:
	global_load_dword v8, v0, s[84:85] offset:1024 sc1
	global_load_dword v9, v0, s[84:85] offset:1280 sc1
	global_load_dword v10, v0, s[84:85] offset:1536 sc1
	global_load_dword v11, v0, s[84:85] offset:1792 sc1
	global_load_dword v12, v0, s[84:85] offset:2048 sc1
	global_load_dword v13, v0, s[84:85] offset:2304 sc1
	global_load_dword v14, v0, s[84:85] offset:2560 sc1
	global_load_dword v15, v0, s[84:85] offset:2816 sc1
	global_load_dword v16, v0, s[84:85] offset:3072 sc1
	global_load_dword v17, v0, s[84:85] offset:3328 sc1
	global_load_dword v18, v0, s[84:85] offset:3584 sc1
	global_load_dword v19, v0, s[84:85] offset:3840 sc1
	global_load_dword v20, v5, s[84:85] offset:0 sc1
	global_load_dword v21, v5, s[84:85] offset:256 sc1
	global_load_dword v22, v5, s[84:85] offset:512 sc1
	global_load_dword v23, v5, s[84:85] offset:768 sc1
	s_waitcnt vmcnt(0)
	s_mov_b32 s9, 0
	s_mov_b32 s10, 0
	s_mov_b32 s11, 0
	v_readfirstlane_b32 s6, v8
	s_add_u32 s9, s9, s6
	s_cmp_lg_u32 s6, 0
	s_addc_u32 s10, s10, 0
	s_cmp_eq_u32 s3, 0
	s_cselect_b32 s11, s6, s11
	v_readfirstlane_b32 s6, v9
	s_add_u32 s9, s9, s6
	s_cmp_lg_u32 s6, 0
	s_addc_u32 s10, s10, 0
	s_cmp_eq_u32 s3, 1
	s_cselect_b32 s11, s6, s11
	v_readfirstlane_b32 s6, v10
	s_add_u32 s9, s9, s6
	s_cmp_lg_u32 s6, 0
	s_addc_u32 s10, s10, 0
	s_cmp_eq_u32 s3, 2
	s_cselect_b32 s11, s6, s11
	v_readfirstlane_b32 s6, v11
	s_add_u32 s9, s9, s6
	s_cmp_lg_u32 s6, 0
	s_addc_u32 s10, s10, 0
	s_cmp_eq_u32 s3, 3
	s_cselect_b32 s11, s6, s11
	v_readfirstlane_b32 s6, v12
	s_add_u32 s9, s9, s6
	s_cmp_lg_u32 s6, 0
	s_addc_u32 s10, s10, 0
	s_cmp_eq_u32 s3, 4
	s_cselect_b32 s11, s6, s11
	v_readfirstlane_b32 s6, v13
	s_add_u32 s9, s9, s6
	s_cmp_lg_u32 s6, 0
	s_addc_u32 s10, s10, 0
	s_cmp_eq_u32 s3, 5
	s_cselect_b32 s11, s6, s11
	v_readfirstlane_b32 s6, v14
	s_add_u32 s9, s9, s6
	s_cmp_lg_u32 s6, 0
	s_addc_u32 s10, s10, 0
	s_cmp_eq_u32 s3, 6
	s_cselect_b32 s11, s6, s11
	v_readfirstlane_b32 s6, v15
	s_add_u32 s9, s9, s6
	s_cmp_lg_u32 s6, 0
	s_addc_u32 s10, s10, 0
	s_cmp_eq_u32 s3, 7
	s_cselect_b32 s11, s6, s11
	v_readfirstlane_b32 s6, v16
	s_add_u32 s9, s9, s6
	s_cmp_lg_u32 s6, 0
	s_addc_u32 s10, s10, 0
	s_cmp_eq_u32 s3, 8
	s_cselect_b32 s11, s6, s11
	v_readfirstlane_b32 s6, v17
	s_add_u32 s9, s9, s6
	s_cmp_lg_u32 s6, 0
	s_addc_u32 s10, s10, 0
	s_cmp_eq_u32 s3, 9
	s_cselect_b32 s11, s6, s11
	v_readfirstlane_b32 s6, v18
	s_add_u32 s9, s9, s6
	s_cmp_lg_u32 s6, 0
	s_addc_u32 s10, s10, 0
	s_cmp_eq_u32 s3, 10
	s_cselect_b32 s11, s6, s11
	v_readfirstlane_b32 s6, v19
	s_add_u32 s9, s9, s6
	s_cmp_lg_u32 s6, 0
	s_addc_u32 s10, s10, 0
	s_cmp_eq_u32 s3, 11
	s_cselect_b32 s11, s6, s11
	v_readfirstlane_b32 s6, v20
	s_add_u32 s9, s9, s6
	s_cmp_lg_u32 s6, 0
	s_addc_u32 s10, s10, 0
	s_cmp_eq_u32 s3, 12
	s_cselect_b32 s11, s6, s11
	v_readfirstlane_b32 s6, v21
	s_add_u32 s9, s9, s6
	s_cmp_lg_u32 s6, 0
	s_addc_u32 s10, s10, 0
	s_cmp_eq_u32 s3, 13
	s_cselect_b32 s11, s6, s11
	v_readfirstlane_b32 s6, v22
	s_add_u32 s9, s9, s6
	s_cmp_lg_u32 s6, 0
	s_addc_u32 s10, s10, 0
	s_cmp_eq_u32 s3, 14
	s_cselect_b32 s11, s6, s11
	v_readfirstlane_b32 s6, v23
	s_add_u32 s9, s9, s6
	s_cmp_lg_u32 s6, 0
	s_addc_u32 s10, s10, 0
	s_cmp_eq_u32 s3, 15
	s_cselect_b32 s11, s6, s11
	s_cmp_eq_u32 s9, s92
	s_cbranch_scc1 .Lgb0_census_ok
	s_sleep 1
	s_add_u32 s15, s15, 1
	s_cmp_lt_u32 s15, 0x10000
	s_cbranch_scc1 .Lgb0_census
.Lgb0_census_ok:
	s_max_u32 s11, s11, 1
	s_max_u32 s10, s10, 1
	v_mov_b32_e32 v6, 0x23fc0
	v_mov_b32_e32 v7, s11
	ds_write_b32 v6, v7
	v_mov_b32_e32 v7, s10
	ds_write_b32 v6, v7 offset:4
	s_add_i32 s14, s8, 0x1000
	v_mov_b32_e32 v4, s14
	global_atomic_add v6, v4, v1, s[84:85] offset:1024 sc0
	s_waitcnt vmcnt(0)
	v_readfirstlane_b32 s6, v6
	s_add_i32 s6, s6, 1
	s_cmp_eq_u32 s6, s11
	s_cbranch_scc0 .Lgb0_poll
	buffer_wbl2 sc1
	s_waitcnt vmcnt(0)
	v_mov_b32_e32 v4, 0x3000
	global_atomic_add v6, v4, v1, s[84:85] offset:1024 sc0
	s_waitcnt vmcnt(0)
	v_readfirstlane_b32 s6, v6
	s_add_i32 s6, s6, 1
	v_mov_b32_e32 v4, 0x3100
	s_cmp_eq_u32 s6, s10
	s_cbranch_scc0 .Lgb0_lpoll
	global_atomic_add v4, v1, s[84:85] offset:1024
	s_branch .Lgb0_lout
.Lgb0_lpoll:
	global_load_dword v6, v4, s[84:85] offset:1024 sc1
	s_waitcnt vmcnt(0)
	v_readfirstlane_b32 s6, v6
	s_cmp_lg_u32 s6, 0
	s_cbranch_scc1 .Lgb0_lout
	s_sleep 1
	s_add_u32 s15, s15, 1
	s_cmp_lt_u32 s15, 0x18000
	s_cbranch_scc1 .Lgb0_lpoll
.Lgb0_lout:
	s_add_i32 s14, s8, 0x2000
	v_mov_b32_e32 v4, s14
	global_atomic_add v4, v1, s[84:85] offset:1024
	s_branch .Lgb0_fin
.Lgb0_poll:
	v_mov_b32_e32 v4, 0x3100

; #define KP (kparams())
;     __host__ __device__ bool next(int i, Unit& u) const {
;         const long L = (long)i * G + c; if (L >= nwg) return false;
;         int wgid = (int)L; { const int q = nwg / NXCD, r = nwg % NXCD, xcd = wgid % NXCD, off = wgid / NXCD; wgid = (xcd < r ? xcd * (q + 1) : r * (q + 1) + (xcd - r) * q) + off; }
;         const int nig = WGM * nN, gid = wgid / nig, fm = gid * WGM, gsz = (nM - fm) < WGM ? (nM - fm) : WGM;
;         u.pm = fm + ((wgid % nig) % gsz); u.pn = (wgid % nig) / gsz; return true;
; __global__ void __launch_bounds__(512) fwd_kernel(Params p_unused) {
;     ...
;     {
;         pg8::Gemm g{(const pg8::bf16_t*)(ws + WS_XB), (const pg8::bf16_t*)(ws + WS_WIN), MT, NPROJ, 1024};
;         pg8::StaticOrder S; S.init(MT, NPROJ, G, bid);
;         EpiIn E{(bfu*)(ws + WS_PROJ), KP.out};
;         pg8::gemm_phase<EpiIn, pg8::StaticOrder, true, true>(lds3, g, S, E);
.Lgb0_done:
	s_mov_b64 exec, s[0:1]
	s_barrier
	v_readlane_b32 s0, v252, 1
	v_readlane_b32 s1, v252, 2
	s_waitcnt vmcnt(1)
	v_mov_b32_e32 v8, v172
	s_cmpk_lt_i32 s2, 0x618
	s_cselect_b64 s[4:5], -1, 0
	s_cmpk_gt_i32 s2, 0x617
	v_readfirstlane_b32 s6, v8
	s_cbranch_scc1 .LBB0_73
	s_ashr_i32 s3, s2, 31
	s_lshr_b32 s3, s3, 29
	s_add_i32 s3, s2, s3
	s_ashr_i32 s7, s3, 3
	s_and_b32 s3, s3, -8
	s_sub_i32 s3, s2, s3
	s_cmp_lt_i32 s3, 0
	s_movk_i32 s8, 0xc4
	s_cselect_b32 s8, s8, 0xc3
	s_mul_i32 s3, s3, s8
	s_add_i32 s3, s3, s7
	s_mul_hi_i32 s7, s3, 0x2aaaaaab
	s_lshr_b32 s8, s7, 31
	s_ashr_i32 s7, s7, 5
	s_add_i32 s7, s7, s8
	s_lshl_b32 s11, s7, 3
	s_sub_i32 s8, 0x41, s11
	s_mulk_i32 s7, 0xc0
	s_min_u32 s14, s8, 8
	s_sub_i32 s3, s3, s7
	s_sext_i32_i16 s7, s3
	v_cvt_f32_ubyte0_e32 v1, s14
	v_cvt_f32_i32_e32 v0, s7
	v_rcp_iflag_f32_e32 v2, v1
	s_ashr_i32 s7, s7, 30
	s_or_b32 s7, s7, 1
	v_mul_f32_e32 v2, v0, v2
	v_trunc_f32_e32 v2, v2
	v_fma_f32 v0, -v2, v1, v0
	v_cvt_i32_f32_e32 v2, v2
	v_cmp_ge_f32_e64 s[8:9], |v0|, v1
	s_and_b64 s[8:9], s[8:9], exec
	s_cselect_b32 s7, s7, 0
	v_readfirstlane_b32 s8, v2
	s_add_i32 s7, s8, s7
	s_sext_i32_i16 s10, s7
	s_mul_i32 s7, s7, s14
	s_sub_i32 s3, s3, s7
	s_sext_i32_i16 s3, s3
	s_add_i32 s8, s11, s3

; __global__ void __launch_bounds__(512) fwd_kernel(Params p_unused) {
;     ...
;     if (bid == 0) for (int i = threadIdx.x; i < CTL_WORDS; i += 512) barw[i] = 0u;
.LBB0_194:
	s_or_b64 exec, exec, s[4:5]
	s_waitcnt vmcnt(0)
	s_barrier
	v_cmp_eq_u32_e32 vcc, 0, v172
	s_and_saveexec_b64 s[4:5], vcc
	s_cbranch_execz .Lctl_tag_skip
	buffer_wbl2 sc1
	s_waitcnt vmcnt(0)
	v_mov_b32_e32 v1, 0
	v_mov_b32_e32 v2, 0x600dc0de
	v_mov_b32_e32 v3, 0x5afe7a61
	global_store_dwordx2 v1, v[2:3], s[84:85] sc1
	s_waitcnt vmcnt(0)
